# attention: next-tile K fragment LDS reads issued earlier in PV (one per gap beside the V reads) so none is outstanding at the per-tile barrier
# speedup vs baseline: 1.0716x; 1.0035x over previous
; #define SBAR() __builtin_amdgcn_sched_barrier(0)
; #define WAIT_BAR(N) asm volatile("s_waitcnt vmcnt(" #N ") lgkmcnt(0)\n\ts_barrier":::"memory")
; __device__ __forceinline__ s16x4 vtr(lds_cptr p){ return __builtin_bit_cast(s16x4,__builtin_amdgcn_ds_read_tr16_b64_v4i16((__attribute__((address_space(3))) v4i16_t*)p)); }
; template<int THRL> __device__ __forceinline__ void attn_unit(int qb,const bf16*Q,const bf16*__restrict__ K,const bf16*__restrict__ V,bf16*O,char*shm){
;     ...
;     bf16x8 kf[8]; kload8(kf,kp0+c0*SLOTB);
;     ...
;     for(int d_=0;d_<4;++d_){ w2l_[d_]=vtr(vp_+(d_*4096+2*1024)); w2h_[d_]=vtr(vp_+(d_*4096+2*1024+512)); }
;     SBAR();
;     #pragma unroll
;     for(int d_=0;d_<4;++d_){ o[d_]=__builtin_amdgcn_mfma_f32_32x32x16_bf16(__builtin_bit_cast(bf16x8,pw0),VFRAG(vl_,vh_,d_*2),o[d_],0,0,0); }
;     SBAR();
;     #pragma unroll
;     for(int d_=0;d_<4;++d_){ w3l_[d_]=vtr(vp_+(d_*4096+3*1024)); w3h_[d_]=vtr(vp_+(d_*4096+3*1024+512)); }
;     SBAR();
;     #pragma unroll
;     for(int d_=0;d_<4;++d_){ o[d_]=__builtin_amdgcn_mfma_f32_32x32x16_bf16(__builtin_bit_cast(bf16x8,pw1),VFRAG(vl_,vh_,d_*2+1),o[d_],0,0,0); }
;     #pragma unroll
;     for(int d_=0;d_<4;++d_){ o[d_]=__builtin_amdgcn_mfma_f32_32x32x16_bf16(__builtin_bit_cast(bf16x8,pw2),VFRAG(w2l_,w2h_,d_),o[d_],0,0,0); }
;     #pragma unroll
;     for(int d_=0;d_<4;++d_){ o[d_]=__builtin_amdgcn_mfma_f32_32x32x16_bf16(__builtin_bit_cast(bf16x8,pw3),VFRAG(w3l_,w3h_,d_),o[d_],0,0,0); }
;     SBAR();
;     ...
;     if(t+2<NT){WAIT_BAR(3);}else{WAIT_BAR(0);}
.Lattn_nodma0:
	s_waitcnt lgkmcnt(12)
	v_mfma_f32_32x32x16_bf16 v[16:31], v[194:197], v[148:151], v[16:31]
	ds_read_b64_tr_b16 v[232:233], v193 offset:38912
	ds_read_b64_tr_b16 v[234:235], v193 offset:39424
	v_exp_f32_e32 v94, v94
	v_exp_f32_e32 v95, v95
	v_cvt_pk_bf16_f32 v200, v92, v93
	v_lshl_add_u32 v164, s27, 13, v189
	s_waitcnt lgkmcnt(10)
	v_mfma_f32_32x32x16_bf16 v[0:15], v[194:197], v[144:147], v[0:15]
	ds_read_b64_tr_b16 v[156:157], v193 offset:39936
	ds_read_b64_tr_b16 v[158:159], v193 offset:40448
	ds_read_b128 v[236:239], v164
	v_cvt_pk_bf16_f32 v201, v94, v95
	v_exp_f32_e32 v96, v96
	v_exp_f32_e32 v97, v97
	v_mfma_f32_32x32x16_bf16 v[48:63], v[198:201], v[140:143], v[48:63]
	ds_read_b64_tr_b16 v[152:153], v193 offset:35840
	ds_read_b64_tr_b16 v[154:155], v193 offset:36352
	ds_read_b128 v[240:243], v164 offset:2048
	v_exp_f32_e32 v98, v98
	v_exp_f32_e32 v99, v99
	v_cvt_pk_bf16_f32 v202, v96, v97
	v_add_f32_e32 v80, v80, v81
	v_mfma_f32_32x32x16_bf16 v[32:47], v[198:201], v[136:139], v[32:47]
	ds_read_b64_tr_b16 v[148:149], v193 offset:31744
	ds_read_b64_tr_b16 v[150:151], v193 offset:32256
	ds_read_b128 v[244:247], v164 offset:4096
	v_exp_f32_e32 v100, v100
	v_exp_f32_e32 v101, v101
	v_cvt_pk_bf16_f32 v203, v98, v99
	v_add_f32_e32 v80, v82, v80
	s_add_i32 s14, s31, 2
	s_cmp_ge_i32 s14, s26
	s_cbranch_scc1 .Lattn_nodma1
	s_lshl_b32 s14, s29, 14
	s_add_i32 s14, s14, s11
	s_mov_b32 m0, s14
	v_lshl_add_u64 v[162:163], v[180:181], 0, s[50:51]
	global_load_lds_dwordx4 v[180:181], off
.Lattn_nodma1:
	v_mfma_f32_32x32x16_bf16 v[16:31], v[198:201], v[132:135], v[16:31]
	ds_read_b64_tr_b16 v[144:145], v193 offset:27648
	ds_read_b64_tr_b16 v[146:147], v193 offset:28160
	ds_read_b128 v[248:251], v164 offset:6144
	v_exp_f32_e32 v102, v102
	v_exp_f32_e32 v103, v103
	v_cvt_pk_bf16_f32 v204, v100, v101
	v_add_f32_e32 v80, v83, v80
	s_waitcnt lgkmcnt(15)
	v_mfma_f32_32x32x16_bf16 v[0:15], v[198:201], v[128:131], v[0:15]
	ds_read_b128 v[194:197], v164 offset:6656
	v_cvt_pk_bf16_f32 v205, v102, v103
	v_exp_f32_e32 v104, v104
	v_exp_f32_e32 v105, v105
	v_add_f32_e32 v80, v84, v80
	v_mfma_f32_32x32x16_bf16 v[48:63], v[202:205], v[210:213], v[48:63]
	ds_read_b128 v[132:135], v164 offset:2560
	v_exp_f32_e32 v106, v106
	v_exp_f32_e32 v107, v107
	v_cvt_pk_bf16_f32 v206, v104, v105
	v_add_f32_e32 v80, v85, v80
	v_mfma_f32_32x32x16_bf16 v[32:47], v[202:205], v[214:217], v[32:47]
	s_add_i32 s14, s31, 2
	s_cmp_ge_i32 s14, s26
	s_cbranch_scc1 .Lattn_nodma2
	s_lshl_b32 s14, s29, 14
	s_add_i32 s14, s14, s11
	s_addk_i32 s14, 0x2000
	s_mov_b32 m0, s14
	s_nop 0
	global_load_lds_dwordx4 v[162:163], off
.Lattn_nodma2:
	ds_read_b128 v[128:131], v164 offset:512
	v_exp_f32_e32 v108, v108
	v_exp_f32_e32 v109, v109
	v_cvt_pk_bf16_f32 v207, v106, v107
	v_add_f32_e32 v80, v86, v80
	s_waitcnt lgkmcnt(15)
	v_mfma_f32_32x32x16_bf16 v[16:31], v[202:205], v[218:221], v[16:31]
	v_exp_f32_e32 v110, v110
	v_exp_f32_e32 v111, v111
	v_cvt_pk_bf16_f32 v208, v108, v109
	v_add_f32_e32 v80, v87, v80
	v_mfma_f32_32x32x16_bf16 v[0:15], v[202:205], v[232:235], v[0:15]
	v_cvt_pk_bf16_f32 v209, v110, v111
	v_add_f32_e32 v81, v96, v97
	v_add_f32_e32 v80, v88, v80
	v_add_f32_e32 v81, v98, v81
	v_add_u32_e32 v192, 64, v192
	v_lshl_add_u64 v[180:181], v[180:181], 0, s[88:89]
	v_lshl_add_u64 v[182:183], v[182:183], 0, s[88:89]
	s_waitcnt lgkmcnt(4)
	v_mfma_f32_32x32x16_bf16 v[48:63], v[206:209], v[144:147], v[48:63]
	ds_read_b128 v[144:147], v164 offset:4608
	v_add_f32_e32 v80, v89, v80
	v_add_f32_e32 v81, v99, v81
	v_add_f32_e32 v80, v90, v80
	v_add_f32_e32 v81, v100, v81
	v_add_f32_e32 v80, v91, v80
	v_add_f32_e32 v81, v101, v81
	s_add_i32 s31, s31, 1
	s_lshl_b32 s14, s27, 14
	v_add_u32_e32 v193, s14, v190
	v_mfma_f32_32x32x16_bf16 v[32:47], v[206:209], v[148:151], v[32:47]
	v_add_f32_e32 v80, v92, v80
	v_add_f32_e32 v81, v102, v81
	v_add_f32_e32 v80, v93, v80
	v_add_f32_e32 v81, v103, v81
	v_add_f32_e32 v80, v94, v80
	v_add_f32_e32 v81, v104, v81
	s_mov_b32 s35, s27
	s_mov_b32 s27, s29
	s_mov_b32 s29, s34
	s_mov_b32 s34, s35
	v_mfma_f32_32x32x16_bf16 v[16:31], v[206:209], v[152:155], v[16:31]
	v_add_f32_e32 v80, v95, v80
	v_add_f32_e32 v81, v105, v81
	v_add_f32_e32 v81, v106, v81
	v_add_f32_e32 v81, v107, v81
	v_add_f32_e32 v81, v108, v81
	v_add_f32_e32 v81, v109, v81
	s_add_i32 s12, s31, 3
	s_cmp_ge_i32 s12, s26
	s_cselect_b64 s[12:13], -1, 0
	v_mfma_f32_32x32x16_bf16 v[0:15], v[206:209], v[156:159], v[0:15]
	v_add_f32_e32 v81, v110, v81
	v_add_f32_e32 v81, v111, v81
	v_add_f32_e32 v80, v81, v80
	v_add_f32_e32 v179, v179, v80
	s_add_i32 s14, s28, s31
	s_cbranch_vccnz .Lattn_tailbar
	s_cmp_eq_u32 s14, 0
	s_waitcnt vmcnt(3) lgkmcnt(0)
	s_barrier
	s_cbranch_scc0 .Lattn_top
	s_branch .LBB0_379
